# k32 + code placement experiment: whole instruction stream shifted by 4 bytes (one s_nop at entry)
# baseline (speedup 1.0000x reference)
_Z14fwd_megakernel6Params:
	s_nop 0
	s_load_dwordx4 s[76:79], s[0:1], 0x80
	s_load_dword s36, s[0:1], 0x90
	s_add_u32 s4, s0, 0x88
	v_and_b32_e32 v1, 0x3ff, v0
	s_addc_u32 s5, s1, 0
	v_readfirstlane_b32 s33, v1
	v_cmp_eq_u32_e64 s[70:71], 0, v1
	s_and_saveexec_b64 s[6:7], s[70:71]
	s_cbranch_execz .LBB0_2
	s_add_i32 s3, 0, 0x23fc0
	v_mov_b32_e32 v2, 0
	v_mov_b32_e32 v3, s3
	s_add_i32 s3, 0, 0x23fc4
	ds_write_b32 v3, v2
	v_mov_b32_e32 v3, s3
	ds_write_b32 v3, v2
